# seam after P0: cooperative-groups grid sync replaced by a two-level barrier with one L2 write-back per XCD
# speedup vs baseline: 1.0093x; 1.0026x over previous
; __device__ __forceinline__ unsigned xb_ld(unsigned* p)              { return __hip_atomic_load(p, __ATOMIC_RELAXED, __HIP_MEMORY_SCOPE_AGENT); }
; __device__ __forceinline__ unsigned xb_add(unsigned* p, unsigned v) { return __hip_atomic_fetch_add(p, v, __ATOMIC_RELAXED, __HIP_MEMORY_SCOPE_AGENT); }
; __device__ __forceinline__ void xcd_barrier_complete(unsigned* bar, unsigned x, unsigned& nloc, unsigned& nx) {
;     const unsigned G = gridDim.x * gridDim.y * gridDim.z;
;     unsigned sum, cnt, mine, sp = 0u;
;     for (;;) {
;         sum = 0u; cnt = 0u; mine = 0u;
; #pragma unroll
;         for (unsigned j = 0; j < 16; ++j) { const unsigned c = xb_ld(&bar[XB_XCNT(j)]); sum += c; cnt += (c > 0u) ? 1u : 0u; mine = (j == x) ? c : mine; }
;         if (sum == G) break;
;         __builtin_amdgcn_s_sleep(1);
;         if ((++sp & 255u) == 0u) { if (xb_ld(&bar[XB_TMO])) break; if (sp > XB_SPIN_CAP) { atomicAdd(&bar[XB_TMO], 1u); break; } }
;     }
;     nloc = mine > 0u ? mine : 1u; nx = cnt > 0u ? cnt : 1u;
; }
; __device__ __forceinline__ void xcd_barrier(const XcdBarrier& b) {
;     asm volatile("s_waitcnt vmcnt(0)" ::: "memory");
;     __syncthreads();
;     if (threadIdx.x == 0) {
;         unsigned* bar = b.bar;
;         __builtin_amdgcn_s_waitcnt(0);
;         unsigned nloc = b.st[0], nx = b.st[1];
;         if (nloc == 0u) { xcd_barrier_complete(bar, b.x, nloc, nx); b.st[0] = nloc; b.st[1] = nx; }
;         const unsigned old = xb_add(&bar[XB_XSUB(b.x)], 1u);
;         const unsigned gen = old / nloc;
;         if (old + 1u == (gen + 1u) * nloc) {
;             __builtin_amdgcn_fence(__ATOMIC_RELEASE, "agent");
;             asm volatile("s_waitcnt vmcnt(0)" ::: "memory");
;             const unsigned og = xb_add(&bar[XB_TOP], 1u);
;             const unsigned tg = og / nx;
;             if (og + 1u == (tg + 1u) * nx) xb_add(&bar[XB_TOPGEN], 1u);
;             else XB_SPIN(xb_ld(&bar[XB_TOPGEN]) == tg, bar);
;             __builtin_amdgcn_fence(__ATOMIC_ACQUIRE, "agent");
;             xb_add(&bar[XB_XGEN(b.x)], 1u);
;             asm volatile("s_waitcnt vmcnt(0)" ::: "memory");
;         } else {
;             XB_SPIN(xb_ld(&bar[XB_XGEN(b.x)]) == gen, bar);
;             __builtin_amdgcn_fence(__ATOMIC_ACQUIRE, "agent");
;             asm volatile("s_waitcnt vmcnt(0)" ::: "memory");
;         }
;     }
;     __syncthreads();
; }
.LBB0_214:
	s_cmp_gt_u32 s19, 1
	s_cselect_b64 s[0:1], -1, 0
	s_and_b64 s[0:1], s[20:21], s[0:1]
	s_andn2_b64 vcc, exec, s[0:1]
	s_cbranch_vccnz .LBB0_226
	s_waitcnt vmcnt(0) lgkmcnt(0)
	s_barrier
	s_and_saveexec_b64 s[0:1], s[78:79]
	s_cbranch_execz .Lg0_done
	v_mov_b32_e32 v0, 0x250d0
	ds_read_b64 v[2:3], v0
	s_getreg_b32 s10, hwreg(HW_REG_XCC_ID, 0, 4)
	s_waitcnt lgkmcnt(0)
	v_readfirstlane_b32 s4, v2
	v_readfirstlane_b32 s5, v3
	s_add_u32 s4, s4, 0x1e600000
	s_addc_u32 s5, s5, 0
	s_and_b32 s10, s10, 15
	s_mov_b32 s11, 0
.Lg0_census:
	s_mov_b32 s12, 0
	s_mov_b32 s13, 0
	s_mov_b32 s14, 0
.Lg0_cj:
	s_lshl_b32 s15, s12, 8
	s_add_i32 s15, s15, 0x400
	v_mov_b32_e32 v0, s15
	global_load_dword v1, v0, s[4:5] sc1
	s_waitcnt vmcnt(0)
	v_readfirstlane_b32 s16, v1
	s_add_i32 s13, s13, s16
	s_cmp_eq_u32 s12, s10
	s_cselect_b32 s14, s16, s14
	s_add_i32 s12, s12, 1
	s_cmp_lt_u32 s12, 16
	s_cbranch_scc1 .Lg0_cj
	s_cmp_eq_u32 s13, s34
	s_cbranch_scc1 .Lg0_arrive
	s_sleep 1
	s_add_i32 s11, s11, 1
	s_cmp_lt_u32 s11, 0x4000
	s_cbranch_scc1 .Lg0_census
.Lg0_arrive:
	s_lshl_b32 s15, s10, 8
	s_add_i32 s15, s15, 0x8000
	v_mov_b32_e32 v0, s15
	v_mov_b32_e32 v1, 1
	global_atomic_add v1, v0, v1, s[4:5] sc0
	s_waitcnt vmcnt(0)
	v_readfirstlane_b32 s16, v1
	s_add_i32 s16, s16, 1
	s_cmp_lg_u32 s16, s14
	s_cbranch_scc1 .Lg0_wait
	buffer_wbl2 sc1
	s_waitcnt vmcnt(0)
	v_mov_b32_e32 v0, 0x9000
	v_mov_b32_e32 v1, s14
	global_atomic_add v0, v1, s[4:5]
.Lg0_wait:
	v_mov_b32_e32 v0, 0x9000
	s_mov_b32 s11, 0
.Lg0_spin:
	global_load_dword v1, v0, s[4:5] sc1
	s_waitcnt vmcnt(0)
	v_readfirstlane_b32 s16, v1
	s_cmp_ge_u32 s16, s34
	s_cbranch_scc1 .Lg0_acq
	s_sleep 1
	s_add_i32 s11, s11, 1
	s_cmp_lt_u32 s11, 0x40000
	s_cbranch_scc1 .Lg0_spin
.Lg0_acq:
	buffer_inv sc1
	s_waitcnt vmcnt(0)
